# GEMM K-loops: the two k-step MFMAs of each accumulator issued back to back (same-accumulator adjacency, same accumulation order); otherwise the lean K-loop of v10
# speedup vs baseline: 1.0084x; 1.0084x over previous
.LBB0_265:
	ds_read_b128 v[154:157], v161
	ds_read_b128 v[164:167], v161 offset:1024
	ds_read_b128 v[168:171], v161 offset:2048
	ds_read_b128 v[172:175], v161 offset:3072
	ds_read_b128 v[176:179], v162
	ds_read_b128 v[180:183], v162 offset:1024
	ds_read_b128 v[184:187], v162 offset:2048
	ds_read_b128 v[188:191], v162 offset:3072
	ds_read_b128 v[192:195], v163
	ds_read_b128 v[196:199], v163 offset:1024
	ds_read_b128 v[200:203], v163 offset:2048
	ds_read_b128 v[204:207], v163 offset:3072
	ds_read_b128 v[208:211], v163 offset:4096
	ds_read_b128 v[212:215], v163 offset:5120
	s_add_i32 m0, s33, 0xc000
	ds_read_b128 v[216:219], v163 offset:6144
	global_load_lds_dwordx4 v146, s[72:73]
	s_add_i32 m0, s33, 0xe000
	ds_read_b128 v[220:223], v163 offset:7168
	global_load_lds_dwordx4 v148, s[72:73]
	s_waitcnt vmcnt(8) lgkmcnt(0)
	s_barrier
	s_setprio 1
	v_mfma_f32_16x16x32_bf16 v[126:129], v[154:157], v[192:195], v[126:129]
	v_mfma_f32_16x16x32_bf16 v[126:129], v[164:167], v[196:199], v[126:129]
	v_mfma_f32_16x16x32_bf16 v[122:125], v[168:171], v[192:195], v[122:125]
	s_add_u32 s12, s72, 0xfff00080
	v_mfma_f32_16x16x32_bf16 v[122:125], v[172:175], v[196:199], v[122:125]
	s_addc_u32 s13, s73, -1
	v_mfma_f32_16x16x32_bf16 v[110:113], v[154:157], v[200:203], v[110:113]
	s_cmp_eq_u32 s83, 60
	v_mfma_f32_16x16x32_bf16 v[110:113], v[164:167], v[204:207], v[110:113]
	s_cselect_b32 s77, s55, s13
	v_mfma_f32_16x16x32_bf16 v[106:109], v[168:171], v[200:203], v[106:109]
	s_cselect_b32 s76, s71, s12
	v_mfma_f32_16x16x32_bf16 v[106:109], v[172:175], v[204:207], v[106:109]
	s_cselect_b32 s75, s53, s82
	v_mfma_f32_16x16x32_bf16 v[94:97], v[154:157], v[208:211], v[94:97]
	s_cselect_b32 s74, s80, s81
	v_mfma_f32_16x16x32_bf16 v[94:97], v[164:167], v[212:215], v[94:97]
	s_add_u32 s98, s74, 0x100000
	v_mfma_f32_16x16x32_bf16 v[90:93], v[168:171], v[208:211], v[90:93]
	s_addc_u32 s99, s75, 0
	v_mfma_f32_16x16x32_bf16 v[90:93], v[172:175], v[212:215], v[90:93]
	s_add_u32 s100, s76, 0x100000
	v_mfma_f32_16x16x32_bf16 v[78:81], v[154:157], v[216:219], v[78:81]
	s_addc_u32 s101, s77, 0
	v_mfma_f32_16x16x32_bf16 v[78:81], v[164:167], v[220:223], v[78:81]
	v_mfma_f32_16x16x32_bf16 v[74:77], v[168:171], v[216:219], v[74:77]
	v_mfma_f32_16x16x32_bf16 v[74:77], v[172:175], v[220:223], v[74:77]
	v_mfma_f32_16x16x32_bf16 v[118:121], v[176:179], v[192:195], v[118:121]
	v_mfma_f32_16x16x32_bf16 v[118:121], v[180:183], v[196:199], v[118:121]
	v_mfma_f32_16x16x32_bf16 v[114:117], v[184:187], v[192:195], v[114:117]
	v_mfma_f32_16x16x32_bf16 v[114:117], v[188:191], v[196:199], v[114:117]
	v_mfma_f32_16x16x32_bf16 v[102:105], v[176:179], v[200:203], v[102:105]
	v_mfma_f32_16x16x32_bf16 v[102:105], v[180:183], v[204:207], v[102:105]
	v_mfma_f32_16x16x32_bf16 v[98:101], v[184:187], v[200:203], v[98:101]
	v_mfma_f32_16x16x32_bf16 v[98:101], v[188:191], v[204:207], v[98:101]
	v_mfma_f32_16x16x32_bf16 v[86:89], v[176:179], v[208:211], v[86:89]
	v_mfma_f32_16x16x32_bf16 v[86:89], v[180:183], v[212:215], v[86:89]
	v_mfma_f32_16x16x32_bf16 v[82:85], v[184:187], v[208:211], v[82:85]
	v_mfma_f32_16x16x32_bf16 v[82:85], v[188:191], v[212:215], v[82:85]
	v_mfma_f32_16x16x32_bf16 v[70:73], v[176:179], v[216:219], v[70:73]
	v_mfma_f32_16x16x32_bf16 v[70:73], v[180:183], v[220:223], v[70:73]
	v_mfma_f32_16x16x32_bf16 v[66:69], v[184:187], v[216:219], v[66:69]
	v_mfma_f32_16x16x32_bf16 v[66:69], v[188:191], v[220:223], v[66:69]
	s_setprio 0
	s_barrier
	ds_read_b128 v[192:195], v163 offset:16384
	ds_read_b128 v[196:199], v163 offset:17408
	s_add_i32 m0, s33, 0x10000
	ds_read_b128 v[200:203], v163 offset:18432
	global_load_lds_dwordx4 v134, s[74:75]
	s_add_i32 m0, s33, 0x12000
	ds_read_b128 v[204:207], v163 offset:19456
	global_load_lds_dwordx4 v130, s[74:75]
	s_add_i32 m0, s33, 0x14000
	ds_read_b128 v[208:211], v163 offset:20480
	global_load_lds_dwordx4 v134, s[98:99]
	s_add_i32 m0, s33, 0x16000
	ds_read_b128 v[212:215], v163 offset:21504
	global_load_lds_dwordx4 v130, s[98:99]
	s_mov_b32 m0, s33
	ds_read_b128 v[216:219], v163 offset:22528
	global_load_lds_dwordx4 v136, s[76:77]
	s_add_i32 m0, s33, 0x2000
	ds_read_b128 v[220:223], v163 offset:23552
	global_load_lds_dwordx4 v132, s[76:77]
	s_waitcnt vmcnt(8) lgkmcnt(0)
	s_barrier
	s_setprio 1
	v_mfma_f32_16x16x32_bf16 v[62:65], v[154:157], v[192:195], v[62:65]
	v_mfma_f32_16x16x32_bf16 v[62:65], v[164:167], v[196:199], v[62:65]
	v_mfma_f32_16x16x32_bf16 v[58:61], v[168:171], v[192:195], v[58:61]
	v_mfma_f32_16x16x32_bf16 v[58:61], v[172:175], v[196:199], v[58:61]
	v_mfma_f32_16x16x32_bf16 v[46:49], v[154:157], v[200:203], v[46:49]
	v_mfma_f32_16x16x32_bf16 v[46:49], v[164:167], v[204:207], v[46:49]
	v_mfma_f32_16x16x32_bf16 v[42:45], v[168:171], v[200:203], v[42:45]
	v_mfma_f32_16x16x32_bf16 v[42:45], v[172:175], v[204:207], v[42:45]
	v_mfma_f32_16x16x32_bf16 v[30:33], v[154:157], v[208:211], v[30:33]
	v_mfma_f32_16x16x32_bf16 v[30:33], v[164:167], v[212:215], v[30:33]
	v_mfma_f32_16x16x32_bf16 v[26:29], v[168:171], v[208:211], v[26:29]
	v_mfma_f32_16x16x32_bf16 v[26:29], v[172:175], v[212:215], v[26:29]
	v_mfma_f32_16x16x32_bf16 v[14:17], v[154:157], v[216:219], v[14:17]
	v_mfma_f32_16x16x32_bf16 v[14:17], v[164:167], v[220:223], v[14:17]
	v_mfma_f32_16x16x32_bf16 v[10:13], v[168:171], v[216:219], v[10:13]
	v_mfma_f32_16x16x32_bf16 v[10:13], v[172:175], v[220:223], v[10:13]
	v_mfma_f32_16x16x32_bf16 v[54:57], v[176:179], v[192:195], v[54:57]
	v_mfma_f32_16x16x32_bf16 v[54:57], v[180:183], v[196:199], v[54:57]
	v_mfma_f32_16x16x32_bf16 v[50:53], v[184:187], v[192:195], v[50:53]
	v_mfma_f32_16x16x32_bf16 v[50:53], v[188:191], v[196:199], v[50:53]
	v_mfma_f32_16x16x32_bf16 v[38:41], v[176:179], v[200:203], v[38:41]
	v_mfma_f32_16x16x32_bf16 v[38:41], v[180:183], v[204:207], v[38:41]
	v_mfma_f32_16x16x32_bf16 v[34:37], v[184:187], v[200:203], v[34:37]
	v_mfma_f32_16x16x32_bf16 v[34:37], v[188:191], v[204:207], v[34:37]
	v_mfma_f32_16x16x32_bf16 v[22:25], v[176:179], v[208:211], v[22:25]
	v_mfma_f32_16x16x32_bf16 v[22:25], v[180:183], v[212:215], v[22:25]
	v_mfma_f32_16x16x32_bf16 v[18:21], v[184:187], v[208:211], v[18:21]
	v_mfma_f32_16x16x32_bf16 v[18:21], v[188:191], v[212:215], v[18:21]
	v_mfma_f32_16x16x32_bf16 v[6:9], v[176:179], v[216:219], v[6:9]
	v_mfma_f32_16x16x32_bf16 v[6:9], v[180:183], v[220:223], v[6:9]
	v_mfma_f32_16x16x32_bf16 v[2:5], v[184:187], v[216:219], v[2:5]
	v_mfma_f32_16x16x32_bf16 v[2:5], v[188:191], v[220:223], v[2:5]
	s_setprio 0
	s_barrier
	ds_read_b128 v[154:157], v226
	ds_read_b128 v[164:167], v226 offset:1024
	ds_read_b128 v[168:171], v226 offset:2048
	ds_read_b128 v[172:175], v226 offset:3072
	ds_read_b128 v[176:179], v227
	ds_read_b128 v[180:183], v227 offset:1024
	ds_read_b128 v[184:187], v227 offset:2048
	ds_read_b128 v[188:191], v227 offset:3072
	ds_read_b128 v[192:195], v163 offset:32768
	ds_read_b128 v[196:199], v163 offset:33792
	ds_read_b128 v[200:203], v163 offset:34816
	ds_read_b128 v[204:207], v163 offset:35840
	ds_read_b128 v[208:211], v163 offset:36864
	ds_read_b128 v[212:215], v163 offset:37888
	s_add_i32 m0, s33, 0x4000
	ds_read_b128 v[216:219], v163 offset:38912
	global_load_lds_dwordx4 v136, s[100:101]
	s_add_i32 m0, s33, 0x6000
	ds_read_b128 v[220:223], v163 offset:39936
	global_load_lds_dwordx4 v132, s[100:101]
	s_waitcnt vmcnt(8) lgkmcnt(0)
	s_barrier
	s_setprio 1
	v_mfma_f32_16x16x32_bf16 v[126:129], v[154:157], v[192:195], v[126:129]
	v_mfma_f32_16x16x32_bf16 v[126:129], v[164:167], v[196:199], v[126:129]
	v_mfma_f32_16x16x32_bf16 v[122:125], v[168:171], v[192:195], v[122:125]
	v_mfma_f32_16x16x32_bf16 v[122:125], v[172:175], v[196:199], v[122:125]
	v_mfma_f32_16x16x32_bf16 v[110:113], v[154:157], v[200:203], v[110:113]
	v_mfma_f32_16x16x32_bf16 v[110:113], v[164:167], v[204:207], v[110:113]
	v_mfma_f32_16x16x32_bf16 v[106:109], v[168:171], v[200:203], v[106:109]
	v_mfma_f32_16x16x32_bf16 v[106:109], v[172:175], v[204:207], v[106:109]
	v_mfma_f32_16x16x32_bf16 v[94:97], v[154:157], v[208:211], v[94:97]
	v_mfma_f32_16x16x32_bf16 v[94:97], v[164:167], v[212:215], v[94:97]
	v_mfma_f32_16x16x32_bf16 v[90:93], v[168:171], v[208:211], v[90:93]
	v_mfma_f32_16x16x32_bf16 v[90:93], v[172:175], v[212:215], v[90:93]
	v_mfma_f32_16x16x32_bf16 v[78:81], v[154:157], v[216:219], v[78:81]
	v_mfma_f32_16x16x32_bf16 v[78:81], v[164:167], v[220:223], v[78:81]
	v_mfma_f32_16x16x32_bf16 v[74:77], v[168:171], v[216:219], v[74:77]
	v_mfma_f32_16x16x32_bf16 v[74:77], v[172:175], v[220:223], v[74:77]
	v_mfma_f32_16x16x32_bf16 v[118:121], v[176:179], v[192:195], v[118:121]
	v_mfma_f32_16x16x32_bf16 v[118:121], v[180:183], v[196:199], v[118:121]
	v_mfma_f32_16x16x32_bf16 v[114:117], v[184:187], v[192:195], v[114:117]
	v_mfma_f32_16x16x32_bf16 v[114:117], v[188:191], v[196:199], v[114:117]
	v_mfma_f32_16x16x32_bf16 v[102:105], v[176:179], v[200:203], v[102:105]
	v_mfma_f32_16x16x32_bf16 v[102:105], v[180:183], v[204:207], v[102:105]
	v_mfma_f32_16x16x32_bf16 v[98:101], v[184:187], v[200:203], v[98:101]
	v_mfma_f32_16x16x32_bf16 v[98:101], v[188:191], v[204:207], v[98:101]
	v_mfma_f32_16x16x32_bf16 v[86:89], v[176:179], v[208:211], v[86:89]
	v_mfma_f32_16x16x32_bf16 v[86:89], v[180:183], v[212:215], v[86:89]
	v_mfma_f32_16x16x32_bf16 v[82:85], v[184:187], v[208:211], v[82:85]
	v_mfma_f32_16x16x32_bf16 v[82:85], v[188:191], v[212:215], v[82:85]
	v_mfma_f32_16x16x32_bf16 v[70:73], v[176:179], v[216:219], v[70:73]
	v_mfma_f32_16x16x32_bf16 v[70:73], v[180:183], v[220:223], v[70:73]
	v_mfma_f32_16x16x32_bf16 v[66:69], v[184:187], v[216:219], v[66:69]
	v_mfma_f32_16x16x32_bf16 v[66:69], v[188:191], v[220:223], v[66:69]
	s_setprio 0
	s_barrier
	ds_read_b128 v[192:195], v163 offset:49152
	ds_read_b128 v[196:199], v163 offset:50176
	s_add_i32 m0, s33, 0x17f80
	ds_read_b128 v[200:203], v163 offset:51200
	global_load_lds_dwordx4 v134, s[74:75] offset:128
	s_add_i32 m0, s33, 0x19f80
	ds_read_b128 v[204:207], v163 offset:52224
	global_load_lds_dwordx4 v130, s[74:75] offset:128
	s_add_i32 m0, s33, 0x1bf80
	ds_read_b128 v[208:211], v163 offset:53248
	global_load_lds_dwordx4 v134, s[98:99] offset:128
	s_add_i32 m0, s33, 0x1df80
	ds_read_b128 v[212:215], v163 offset:54272
	global_load_lds_dwordx4 v130, s[98:99] offset:128
	s_add_i32 m0, s33, 0x7f80
	ds_read_b128 v[216:219], v163 offset:55296
	global_load_lds_dwordx4 v136, s[76:77] offset:128
	s_add_i32 m0, s33, 0x9f80
	ds_read_b128 v[220:223], v163 offset:56320
	global_load_lds_dwordx4 v132, s[76:77] offset:128
	s_waitcnt vmcnt(8) lgkmcnt(0)
	s_barrier
	s_setprio 1
	v_mfma_f32_16x16x32_bf16 v[62:65], v[154:157], v[192:195], v[62:65]
	v_mfma_f32_16x16x32_bf16 v[62:65], v[164:167], v[196:199], v[62:65]
	v_mfma_f32_16x16x32_bf16 v[58:61], v[168:171], v[192:195], v[58:61]
	v_mfma_f32_16x16x32_bf16 v[58:61], v[172:175], v[196:199], v[58:61]
	v_mfma_f32_16x16x32_bf16 v[46:49], v[154:157], v[200:203], v[46:49]
	v_mfma_f32_16x16x32_bf16 v[46:49], v[164:167], v[204:207], v[46:49]
	v_mfma_f32_16x16x32_bf16 v[42:45], v[168:171], v[200:203], v[42:45]
	v_mfma_f32_16x16x32_bf16 v[42:45], v[172:175], v[204:207], v[42:45]
	v_mfma_f32_16x16x32_bf16 v[30:33], v[154:157], v[208:211], v[30:33]
	v_mfma_f32_16x16x32_bf16 v[30:33], v[164:167], v[212:215], v[30:33]
	v_mfma_f32_16x16x32_bf16 v[26:29], v[168:171], v[208:211], v[26:29]
	v_mfma_f32_16x16x32_bf16 v[26:29], v[172:175], v[212:215], v[26:29]
	v_mfma_f32_16x16x32_bf16 v[14:17], v[154:157], v[216:219], v[14:17]
	v_mfma_f32_16x16x32_bf16 v[14:17], v[164:167], v[220:223], v[14:17]
	v_mfma_f32_16x16x32_bf16 v[10:13], v[168:171], v[216:219], v[10:13]
	v_mfma_f32_16x16x32_bf16 v[10:13], v[172:175], v[220:223], v[10:13]
	v_mfma_f32_16x16x32_bf16 v[54:57], v[176:179], v[192:195], v[54:57]
	v_mfma_f32_16x16x32_bf16 v[54:57], v[180:183], v[196:199], v[54:57]
	v_mfma_f32_16x16x32_bf16 v[50:53], v[184:187], v[192:195], v[50:53]
	v_mfma_f32_16x16x32_bf16 v[50:53], v[188:191], v[196:199], v[50:53]
	v_mfma_f32_16x16x32_bf16 v[38:41], v[176:179], v[200:203], v[38:41]
	v_mfma_f32_16x16x32_bf16 v[38:41], v[180:183], v[204:207], v[38:41]
	v_mfma_f32_16x16x32_bf16 v[34:37], v[184:187], v[200:203], v[34:37]
	v_mfma_f32_16x16x32_bf16 v[34:37], v[188:191], v[204:207], v[34:37]
	v_mfma_f32_16x16x32_bf16 v[22:25], v[176:179], v[208:211], v[22:25]
	v_mfma_f32_16x16x32_bf16 v[22:25], v[180:183], v[212:215], v[22:25]
	s_add_i32 s83, s83, 2
	v_mfma_f32_16x16x32_bf16 v[18:21], v[184:187], v[208:211], v[18:21]
	s_add_u32 s72, s72, 0x100
	v_mfma_f32_16x16x32_bf16 v[18:21], v[188:191], v[212:215], v[18:21]
	s_addc_u32 s73, s73, 0
	v_mfma_f32_16x16x32_bf16 v[6:9], v[176:179], v[216:219], v[6:9]
	s_add_u32 s81, s81, 0x100
	v_mfma_f32_16x16x32_bf16 v[6:9], v[180:183], v[220:223], v[6:9]
	s_addc_u32 s82, s82, 0
	v_mfma_f32_16x16x32_bf16 v[2:5], v[184:187], v[216:219], v[2:5]
	s_cmp_gt_u32 s83, 61
	v_mfma_f32_16x16x32_bf16 v[2:5], v[188:191], v[220:223], v[2:5]
	s_setprio 0
	s_barrier
	s_cbranch_scc0 .LBB0_265
	s_and_b64 vcc, exec, s[46:47]
	s_cbranch_vccz .LBB0_268
	s_barrier

.LBB0_510:
	ds_read_b128 v[146:149], v152
	ds_read_b128 v[156:159], v152 offset:1024
	ds_read_b128 v[160:163], v152 offset:2048
	ds_read_b128 v[164:167], v152 offset:3072
	ds_read_b128 v[168:171], v153
	ds_read_b128 v[172:175], v153 offset:1024
	ds_read_b128 v[176:179], v153 offset:2048
	ds_read_b128 v[180:183], v153 offset:3072
	ds_read_b128 v[184:187], v154
	ds_read_b128 v[188:191], v154 offset:1024
	ds_read_b128 v[192:195], v154 offset:2048
	ds_read_b128 v[196:199], v154 offset:3072
	ds_read_b128 v[206:209], v154 offset:4096
	ds_read_b128 v[210:213], v154 offset:5120
	s_add_i32 m0, s1, 0xc000
	ds_read_b128 v[214:217], v154 offset:6144
	global_load_lds_dwordx4 v138, s[52:53]
	s_add_i32 m0, s1, 0xe000
	ds_read_b128 v[218:221], v154 offset:7168
	global_load_lds_dwordx4 v140, s[52:53]
	s_waitcnt vmcnt(8) lgkmcnt(0)
	s_barrier
	s_setprio 1
	v_mfma_f32_16x16x32_bf16 v[126:129], v[146:149], v[184:187], v[126:129]
	v_mfma_f32_16x16x32_bf16 v[126:129], v[156:159], v[188:191], v[126:129]
	v_mfma_f32_16x16x32_bf16 v[122:125], v[160:163], v[184:187], v[122:125]
	s_add_u32 s34, s52, 0xfff00080
	v_mfma_f32_16x16x32_bf16 v[122:125], v[164:167], v[188:191], v[122:125]
	s_addc_u32 s36, s53, -1
	v_mfma_f32_16x16x32_bf16 v[110:113], v[146:149], v[192:195], v[110:113]
	s_cmp_eq_u32 s62, 60
	v_mfma_f32_16x16x32_bf16 v[110:113], v[156:159], v[196:199], v[110:113]
	s_cselect_b32 s67, s45, s36
	v_mfma_f32_16x16x32_bf16 v[106:109], v[160:163], v[192:195], v[106:109]
	s_cselect_b32 s66, s51, s34
	v_mfma_f32_16x16x32_bf16 v[106:109], v[164:167], v[196:199], v[106:109]
	s_cselect_b32 s55, s23, s61
	v_mfma_f32_16x16x32_bf16 v[94:97], v[146:149], v[206:209], v[94:97]
	s_cselect_b32 s54, s59, s60
	v_mfma_f32_16x16x32_bf16 v[94:97], v[156:159], v[210:213], v[94:97]
	s_add_u32 s98, s54, 0x100000
	v_mfma_f32_16x16x32_bf16 v[90:93], v[160:163], v[206:209], v[90:93]
	s_addc_u32 s99, s55, 0
	v_mfma_f32_16x16x32_bf16 v[90:93], v[164:167], v[210:213], v[90:93]
	s_add_u32 s100, s66, 0x100000
	v_mfma_f32_16x16x32_bf16 v[78:81], v[146:149], v[214:217], v[78:81]
	s_addc_u32 s101, s67, 0
	v_mfma_f32_16x16x32_bf16 v[78:81], v[156:159], v[218:221], v[78:81]
	v_mfma_f32_16x16x32_bf16 v[74:77], v[160:163], v[214:217], v[74:77]
	v_mfma_f32_16x16x32_bf16 v[74:77], v[164:167], v[218:221], v[74:77]
	v_mfma_f32_16x16x32_bf16 v[118:121], v[168:171], v[184:187], v[118:121]
	v_mfma_f32_16x16x32_bf16 v[118:121], v[172:175], v[188:191], v[118:121]
	v_mfma_f32_16x16x32_bf16 v[114:117], v[176:179], v[184:187], v[114:117]
	v_mfma_f32_16x16x32_bf16 v[114:117], v[180:183], v[188:191], v[114:117]
	v_mfma_f32_16x16x32_bf16 v[102:105], v[168:171], v[192:195], v[102:105]
	v_mfma_f32_16x16x32_bf16 v[102:105], v[172:175], v[196:199], v[102:105]
	v_mfma_f32_16x16x32_bf16 v[98:101], v[176:179], v[192:195], v[98:101]
	v_mfma_f32_16x16x32_bf16 v[98:101], v[180:183], v[196:199], v[98:101]
	v_mfma_f32_16x16x32_bf16 v[86:89], v[168:171], v[206:209], v[86:89]
	v_mfma_f32_16x16x32_bf16 v[86:89], v[172:175], v[210:213], v[86:89]
	v_mfma_f32_16x16x32_bf16 v[82:85], v[176:179], v[206:209], v[82:85]
	v_mfma_f32_16x16x32_bf16 v[82:85], v[180:183], v[210:213], v[82:85]
	v_mfma_f32_16x16x32_bf16 v[70:73], v[168:171], v[214:217], v[70:73]
	v_mfma_f32_16x16x32_bf16 v[70:73], v[172:175], v[218:221], v[70:73]
	v_mfma_f32_16x16x32_bf16 v[66:69], v[176:179], v[214:217], v[66:69]
	v_mfma_f32_16x16x32_bf16 v[66:69], v[180:183], v[218:221], v[66:69]
	s_setprio 0
	s_barrier
	ds_read_b128 v[184:187], v154 offset:16384
	ds_read_b128 v[188:191], v154 offset:17408
	s_add_i32 m0, s1, 0x10000
	ds_read_b128 v[192:195], v154 offset:18432
	global_load_lds_dwordx4 v132, s[54:55]
	s_add_i32 m0, s1, 0x12000
	ds_read_b128 v[196:199], v154 offset:19456
	global_load_lds_dwordx4 v136, s[54:55]
	s_add_i32 m0, s1, 0x14000
	ds_read_b128 v[206:209], v154 offset:20480
	global_load_lds_dwordx4 v132, s[98:99]
	s_add_i32 m0, s1, 0x16000
	ds_read_b128 v[210:213], v154 offset:21504
	global_load_lds_dwordx4 v136, s[98:99]
	s_mov_b32 m0, s1
	ds_read_b128 v[214:217], v154 offset:22528
	global_load_lds_dwordx4 v130, s[66:67]
	s_add_i32 m0, s1, 0x2000
	ds_read_b128 v[218:221], v154 offset:23552
	global_load_lds_dwordx4 v134, s[66:67]
	s_waitcnt vmcnt(8) lgkmcnt(0)
	s_barrier
	s_setprio 1
	v_mfma_f32_16x16x32_bf16 v[62:65], v[146:149], v[184:187], v[62:65]
	v_mfma_f32_16x16x32_bf16 v[62:65], v[156:159], v[188:191], v[62:65]
	v_mfma_f32_16x16x32_bf16 v[58:61], v[160:163], v[184:187], v[58:61]
	v_mfma_f32_16x16x32_bf16 v[58:61], v[164:167], v[188:191], v[58:61]
	v_mfma_f32_16x16x32_bf16 v[46:49], v[146:149], v[192:195], v[46:49]
	v_mfma_f32_16x16x32_bf16 v[46:49], v[156:159], v[196:199], v[46:49]
	v_mfma_f32_16x16x32_bf16 v[42:45], v[160:163], v[192:195], v[42:45]
	v_mfma_f32_16x16x32_bf16 v[42:45], v[164:167], v[196:199], v[42:45]
	v_mfma_f32_16x16x32_bf16 v[30:33], v[146:149], v[206:209], v[30:33]
	v_mfma_f32_16x16x32_bf16 v[30:33], v[156:159], v[210:213], v[30:33]
	v_mfma_f32_16x16x32_bf16 v[26:29], v[160:163], v[206:209], v[26:29]
	v_mfma_f32_16x16x32_bf16 v[26:29], v[164:167], v[210:213], v[26:29]
	v_mfma_f32_16x16x32_bf16 v[14:17], v[146:149], v[214:217], v[14:17]
	v_mfma_f32_16x16x32_bf16 v[14:17], v[156:159], v[218:221], v[14:17]
	v_mfma_f32_16x16x32_bf16 v[10:13], v[160:163], v[214:217], v[10:13]
	v_mfma_f32_16x16x32_bf16 v[10:13], v[164:167], v[218:221], v[10:13]
	v_mfma_f32_16x16x32_bf16 v[54:57], v[168:171], v[184:187], v[54:57]
	v_mfma_f32_16x16x32_bf16 v[54:57], v[172:175], v[188:191], v[54:57]
	v_mfma_f32_16x16x32_bf16 v[50:53], v[176:179], v[184:187], v[50:53]
	v_mfma_f32_16x16x32_bf16 v[50:53], v[180:183], v[188:191], v[50:53]
	v_mfma_f32_16x16x32_bf16 v[38:41], v[168:171], v[192:195], v[38:41]
	v_mfma_f32_16x16x32_bf16 v[38:41], v[172:175], v[196:199], v[38:41]
	v_mfma_f32_16x16x32_bf16 v[34:37], v[176:179], v[192:195], v[34:37]
	v_mfma_f32_16x16x32_bf16 v[34:37], v[180:183], v[196:199], v[34:37]
	v_mfma_f32_16x16x32_bf16 v[22:25], v[168:171], v[206:209], v[22:25]
	v_mfma_f32_16x16x32_bf16 v[22:25], v[172:175], v[210:213], v[22:25]
	v_mfma_f32_16x16x32_bf16 v[18:21], v[176:179], v[206:209], v[18:21]
	v_mfma_f32_16x16x32_bf16 v[18:21], v[180:183], v[210:213], v[18:21]
	v_mfma_f32_16x16x32_bf16 v[6:9], v[168:171], v[214:217], v[6:9]
	v_mfma_f32_16x16x32_bf16 v[6:9], v[172:175], v[218:221], v[6:9]
	v_mfma_f32_16x16x32_bf16 v[2:5], v[176:179], v[214:217], v[2:5]
	v_mfma_f32_16x16x32_bf16 v[2:5], v[180:183], v[218:221], v[2:5]
	s_setprio 0
	s_barrier
	ds_read_b128 v[146:149], v226
	ds_read_b128 v[156:159], v226 offset:1024
	ds_read_b128 v[160:163], v226 offset:2048
	ds_read_b128 v[164:167], v226 offset:3072
	ds_read_b128 v[168:171], v227
	ds_read_b128 v[172:175], v227 offset:1024
	ds_read_b128 v[176:179], v227 offset:2048
	ds_read_b128 v[180:183], v227 offset:3072
	ds_read_b128 v[184:187], v154 offset:32768
	ds_read_b128 v[188:191], v154 offset:33792
	ds_read_b128 v[192:195], v154 offset:34816
	ds_read_b128 v[196:199], v154 offset:35840
	ds_read_b128 v[206:209], v154 offset:36864
	ds_read_b128 v[210:213], v154 offset:37888
	s_add_i32 m0, s1, 0x4000
	ds_read_b128 v[214:217], v154 offset:38912
	global_load_lds_dwordx4 v130, s[100:101]
	s_add_i32 m0, s1, 0x6000
	ds_read_b128 v[218:221], v154 offset:39936
	global_load_lds_dwordx4 v134, s[100:101]
	s_waitcnt vmcnt(8) lgkmcnt(0)
	s_barrier
	s_setprio 1
	v_mfma_f32_16x16x32_bf16 v[126:129], v[146:149], v[184:187], v[126:129]
	v_mfma_f32_16x16x32_bf16 v[126:129], v[156:159], v[188:191], v[126:129]
	v_mfma_f32_16x16x32_bf16 v[122:125], v[160:163], v[184:187], v[122:125]
	v_mfma_f32_16x16x32_bf16 v[122:125], v[164:167], v[188:191], v[122:125]
	v_mfma_f32_16x16x32_bf16 v[110:113], v[146:149], v[192:195], v[110:113]
	v_mfma_f32_16x16x32_bf16 v[110:113], v[156:159], v[196:199], v[110:113]
	v_mfma_f32_16x16x32_bf16 v[106:109], v[160:163], v[192:195], v[106:109]
	v_mfma_f32_16x16x32_bf16 v[106:109], v[164:167], v[196:199], v[106:109]
	v_mfma_f32_16x16x32_bf16 v[94:97], v[146:149], v[206:209], v[94:97]
	v_mfma_f32_16x16x32_bf16 v[94:97], v[156:159], v[210:213], v[94:97]
	v_mfma_f32_16x16x32_bf16 v[90:93], v[160:163], v[206:209], v[90:93]
	v_mfma_f32_16x16x32_bf16 v[90:93], v[164:167], v[210:213], v[90:93]
	v_mfma_f32_16x16x32_bf16 v[78:81], v[146:149], v[214:217], v[78:81]
	v_mfma_f32_16x16x32_bf16 v[78:81], v[156:159], v[218:221], v[78:81]
	v_mfma_f32_16x16x32_bf16 v[74:77], v[160:163], v[214:217], v[74:77]
	v_mfma_f32_16x16x32_bf16 v[74:77], v[164:167], v[218:221], v[74:77]
	v_mfma_f32_16x16x32_bf16 v[118:121], v[168:171], v[184:187], v[118:121]
	v_mfma_f32_16x16x32_bf16 v[118:121], v[172:175], v[188:191], v[118:121]
	v_mfma_f32_16x16x32_bf16 v[114:117], v[176:179], v[184:187], v[114:117]
	v_mfma_f32_16x16x32_bf16 v[114:117], v[180:183], v[188:191], v[114:117]
	v_mfma_f32_16x16x32_bf16 v[102:105], v[168:171], v[192:195], v[102:105]
	v_mfma_f32_16x16x32_bf16 v[102:105], v[172:175], v[196:199], v[102:105]
	v_mfma_f32_16x16x32_bf16 v[98:101], v[176:179], v[192:195], v[98:101]
	v_mfma_f32_16x16x32_bf16 v[98:101], v[180:183], v[196:199], v[98:101]
	v_mfma_f32_16x16x32_bf16 v[86:89], v[168:171], v[206:209], v[86:89]
	v_mfma_f32_16x16x32_bf16 v[86:89], v[172:175], v[210:213], v[86:89]
	v_mfma_f32_16x16x32_bf16 v[82:85], v[176:179], v[206:209], v[82:85]
	v_mfma_f32_16x16x32_bf16 v[82:85], v[180:183], v[210:213], v[82:85]
	v_mfma_f32_16x16x32_bf16 v[70:73], v[168:171], v[214:217], v[70:73]
	v_mfma_f32_16x16x32_bf16 v[70:73], v[172:175], v[218:221], v[70:73]
	v_mfma_f32_16x16x32_bf16 v[66:69], v[176:179], v[214:217], v[66:69]
	v_mfma_f32_16x16x32_bf16 v[66:69], v[180:183], v[218:221], v[66:69]
	s_setprio 0
	s_barrier
	ds_read_b128 v[184:187], v154 offset:49152
	ds_read_b128 v[188:191], v154 offset:50176
	s_add_i32 m0, s1, 0x17f80
	ds_read_b128 v[192:195], v154 offset:51200
	global_load_lds_dwordx4 v132, s[54:55] offset:128
	s_add_i32 m0, s1, 0x19f80
	ds_read_b128 v[196:199], v154 offset:52224
	global_load_lds_dwordx4 v136, s[54:55] offset:128
	s_add_i32 m0, s1, 0x1bf80
	ds_read_b128 v[206:209], v154 offset:53248
	global_load_lds_dwordx4 v132, s[98:99] offset:128
	s_add_i32 m0, s1, 0x1df80
	ds_read_b128 v[210:213], v154 offset:54272
	global_load_lds_dwordx4 v136, s[98:99] offset:128
	s_add_i32 m0, s1, 0x7f80
	ds_read_b128 v[214:217], v154 offset:55296
	global_load_lds_dwordx4 v130, s[66:67] offset:128
	s_add_i32 m0, s1, 0x9f80
	ds_read_b128 v[218:221], v154 offset:56320
	global_load_lds_dwordx4 v134, s[66:67] offset:128
	s_waitcnt vmcnt(8) lgkmcnt(0)
	s_barrier
	s_setprio 1
	v_mfma_f32_16x16x32_bf16 v[62:65], v[146:149], v[184:187], v[62:65]
	v_mfma_f32_16x16x32_bf16 v[62:65], v[156:159], v[188:191], v[62:65]
	v_mfma_f32_16x16x32_bf16 v[58:61], v[160:163], v[184:187], v[58:61]
	v_mfma_f32_16x16x32_bf16 v[58:61], v[164:167], v[188:191], v[58:61]
	v_mfma_f32_16x16x32_bf16 v[46:49], v[146:149], v[192:195], v[46:49]
	v_mfma_f32_16x16x32_bf16 v[46:49], v[156:159], v[196:199], v[46:49]
	v_mfma_f32_16x16x32_bf16 v[42:45], v[160:163], v[192:195], v[42:45]
	v_mfma_f32_16x16x32_bf16 v[42:45], v[164:167], v[196:199], v[42:45]
	v_mfma_f32_16x16x32_bf16 v[30:33], v[146:149], v[206:209], v[30:33]
	v_mfma_f32_16x16x32_bf16 v[30:33], v[156:159], v[210:213], v[30:33]
	v_mfma_f32_16x16x32_bf16 v[26:29], v[160:163], v[206:209], v[26:29]
	v_mfma_f32_16x16x32_bf16 v[26:29], v[164:167], v[210:213], v[26:29]
	v_mfma_f32_16x16x32_bf16 v[14:17], v[146:149], v[214:217], v[14:17]
	v_mfma_f32_16x16x32_bf16 v[14:17], v[156:159], v[218:221], v[14:17]
	v_mfma_f32_16x16x32_bf16 v[10:13], v[160:163], v[214:217], v[10:13]
	v_mfma_f32_16x16x32_bf16 v[10:13], v[164:167], v[218:221], v[10:13]
	v_mfma_f32_16x16x32_bf16 v[54:57], v[168:171], v[184:187], v[54:57]
	v_mfma_f32_16x16x32_bf16 v[54:57], v[172:175], v[188:191], v[54:57]
	v_mfma_f32_16x16x32_bf16 v[50:53], v[176:179], v[184:187], v[50:53]
	v_mfma_f32_16x16x32_bf16 v[50:53], v[180:183], v[188:191], v[50:53]
	v_mfma_f32_16x16x32_bf16 v[38:41], v[168:171], v[192:195], v[38:41]
	v_mfma_f32_16x16x32_bf16 v[38:41], v[172:175], v[196:199], v[38:41]
	v_mfma_f32_16x16x32_bf16 v[34:37], v[176:179], v[192:195], v[34:37]
	v_mfma_f32_16x16x32_bf16 v[34:37], v[180:183], v[196:199], v[34:37]
	v_mfma_f32_16x16x32_bf16 v[22:25], v[168:171], v[206:209], v[22:25]
	v_mfma_f32_16x16x32_bf16 v[22:25], v[172:175], v[210:213], v[22:25]
	s_add_i32 s62, s62, 2
	v_mfma_f32_16x16x32_bf16 v[18:21], v[176:179], v[206:209], v[18:21]
	s_add_u32 s60, s60, 0x100
	v_mfma_f32_16x16x32_bf16 v[18:21], v[180:183], v[210:213], v[18:21]
	s_addc_u32 s61, s61, 0
	v_mfma_f32_16x16x32_bf16 v[6:9], v[168:171], v[214:217], v[6:9]
	s_add_u32 s52, s52, 0x100
	v_mfma_f32_16x16x32_bf16 v[6:9], v[172:175], v[218:221], v[6:9]
	s_addc_u32 s53, s53, 0
	v_mfma_f32_16x16x32_bf16 v[2:5], v[176:179], v[214:217], v[2:5]
	s_cmp_gt_u32 s62, 61
	v_mfma_f32_16x16x32_bf16 v[2:5], v[180:183], v[218:221], v[2:5]
	s_setprio 0
	s_barrier
	s_cbranch_scc0 .LBB0_510
	s_and_b64 vcc, exec, s[20:21]
	s_cbranch_vccz .LBB0_513
	s_barrier

.LBB0_651:
	ds_read_b128 v[130:133], v210
	ds_read_b128 v[134:137], v210 offset:1024
	ds_read_b128 v[138:141], v210 offset:2048
	ds_read_b128 v[142:145], v210 offset:3072
	ds_read_b128 v[146:149], v211
	ds_read_b128 v[150:153], v211 offset:1024
	ds_read_b128 v[154:157], v211 offset:2048
	ds_read_b128 v[158:161], v211 offset:3072
	ds_read_b128 v[162:165], v212
	ds_read_b128 v[166:169], v212 offset:1024
	ds_read_b128 v[188:191], v212 offset:2048
	ds_read_b128 v[192:195], v212 offset:3072
	ds_read_b128 v[196:199], v212 offset:4096
	ds_read_b128 v[214:217], v212 offset:5120
	s_add_i32 m0, s39, 0xc000
	ds_read_b128 v[218:221], v212 offset:6144
	global_load_lds_dwordx4 v180, s[88:89]
	s_add_i32 m0, s39, 0xe000
	ds_read_b128 v[222:225], v212 offset:7168
	global_load_lds_dwordx4 v182, s[88:89]
	s_waitcnt vmcnt(8) lgkmcnt(0)
	s_barrier
	s_setprio 1
	v_mfma_f32_16x16x32_bf16 v[126:129], v[130:133], v[162:165], v[126:129]
	v_mfma_f32_16x16x32_bf16 v[126:129], v[134:137], v[166:169], v[126:129]
	v_mfma_f32_16x16x32_bf16 v[62:65], v[138:141], v[162:165], v[62:65]
	s_add_u32 s90, s88, 0x100
	v_mfma_f32_16x16x32_bf16 v[62:65], v[142:145], v[166:169], v[62:65]
	s_addc_u32 s91, s89, 0
	v_mfma_f32_16x16x32_bf16 v[122:125], v[130:133], v[188:191], v[122:125]
	s_cmp_eq_u32 s66, 60
	v_mfma_f32_16x16x32_bf16 v[122:125], v[134:137], v[192:195], v[122:125]
	s_cselect_b32 s95, s79, s91
	v_mfma_f32_16x16x32_bf16 v[58:61], v[138:141], v[188:191], v[58:61]
	s_cselect_b32 s94, s85, s90
	v_mfma_f32_16x16x32_bf16 v[58:61], v[142:145], v[192:195], v[58:61]
	s_cselect_b32 s93, s77, vcc_hi
	v_mfma_f32_16x16x32_bf16 v[110:113], v[130:133], v[196:199], v[110:113]
	s_cselect_b32 s92, s87, vcc_lo
	v_mfma_f32_16x16x32_bf16 v[110:113], v[134:137], v[214:217], v[110:113]
	s_add_u32 s98, s92, 0x100000
	v_mfma_f32_16x16x32_bf16 v[50:53], v[138:141], v[196:199], v[50:53]
	s_addc_u32 s99, s93, 0
	v_mfma_f32_16x16x32_bf16 v[50:53], v[142:145], v[214:217], v[50:53]
	s_add_u32 s100, s94, 0x100000
	v_mfma_f32_16x16x32_bf16 v[106:109], v[130:133], v[218:221], v[106:109]
	s_addc_u32 s101, s95, 0
	v_mfma_f32_16x16x32_bf16 v[106:109], v[134:137], v[222:225], v[106:109]
	v_mfma_f32_16x16x32_bf16 v[42:45], v[138:141], v[218:221], v[42:45]
	v_mfma_f32_16x16x32_bf16 v[42:45], v[142:145], v[222:225], v[42:45]
	v_mfma_f32_16x16x32_bf16 v[118:121], v[146:149], v[162:165], v[118:121]
	v_mfma_f32_16x16x32_bf16 v[118:121], v[150:153], v[166:169], v[118:121]
	v_mfma_f32_16x16x32_bf16 v[54:57], v[154:157], v[162:165], v[54:57]
	v_mfma_f32_16x16x32_bf16 v[54:57], v[158:161], v[166:169], v[54:57]
	v_mfma_f32_16x16x32_bf16 v[114:117], v[146:149], v[188:191], v[114:117]
	v_mfma_f32_16x16x32_bf16 v[114:117], v[150:153], v[192:195], v[114:117]
	v_mfma_f32_16x16x32_bf16 v[46:49], v[154:157], v[188:191], v[46:49]
	v_mfma_f32_16x16x32_bf16 v[46:49], v[158:161], v[192:195], v[46:49]
	v_mfma_f32_16x16x32_bf16 v[102:105], v[146:149], v[196:199], v[102:105]
	v_mfma_f32_16x16x32_bf16 v[102:105], v[150:153], v[214:217], v[102:105]
	v_mfma_f32_16x16x32_bf16 v[38:41], v[154:157], v[196:199], v[38:41]
	v_mfma_f32_16x16x32_bf16 v[38:41], v[158:161], v[214:217], v[38:41]
	v_mfma_f32_16x16x32_bf16 v[98:101], v[146:149], v[218:221], v[98:101]
	v_mfma_f32_16x16x32_bf16 v[98:101], v[150:153], v[222:225], v[98:101]
	v_mfma_f32_16x16x32_bf16 v[34:37], v[154:157], v[218:221], v[34:37]
	v_mfma_f32_16x16x32_bf16 v[34:37], v[158:161], v[222:225], v[34:37]
	s_setprio 0
	s_barrier
	ds_read_b128 v[162:165], v212 offset:16384
	ds_read_b128 v[166:169], v212 offset:17408
	s_add_i32 m0, s39, 0x10000
	ds_read_b128 v[188:191], v212 offset:18432
	global_load_lds_dwordx4 v172, s[92:93]
	s_add_i32 m0, s39, 0x12000
	ds_read_b128 v[192:195], v212 offset:19456
	global_load_lds_dwordx4 v176, s[92:93]
	s_add_i32 m0, s39, 0x14000
	ds_read_b128 v[196:199], v212 offset:20480
	global_load_lds_dwordx4 v172, s[98:99]
	s_add_i32 m0, s39, 0x16000
	ds_read_b128 v[214:217], v212 offset:21504
	global_load_lds_dwordx4 v176, s[98:99]
	s_mov_b32 m0, s39
	ds_read_b128 v[218:221], v212 offset:22528
	global_load_lds_dwordx4 v170, s[94:95]
	s_add_i32 m0, s39, 0x2000
	ds_read_b128 v[222:225], v212 offset:23552
	global_load_lds_dwordx4 v174, s[94:95]
	s_waitcnt vmcnt(8) lgkmcnt(0)
	s_barrier
	s_setprio 1
	v_mfma_f32_16x16x32_bf16 v[94:97], v[130:133], v[162:165], v[94:97]
	v_mfma_f32_16x16x32_bf16 v[94:97], v[134:137], v[166:169], v[94:97]
	v_mfma_f32_16x16x32_bf16 v[30:33], v[138:141], v[162:165], v[30:33]
	v_mfma_f32_16x16x32_bf16 v[30:33], v[142:145], v[166:169], v[30:33]
	v_mfma_f32_16x16x32_bf16 v[90:93], v[130:133], v[188:191], v[90:93]
	v_mfma_f32_16x16x32_bf16 v[90:93], v[134:137], v[192:195], v[90:93]
	v_mfma_f32_16x16x32_bf16 v[26:29], v[138:141], v[188:191], v[26:29]
	v_mfma_f32_16x16x32_bf16 v[26:29], v[142:145], v[192:195], v[26:29]
	v_mfma_f32_16x16x32_bf16 v[82:85], v[130:133], v[196:199], v[82:85]
	v_mfma_f32_16x16x32_bf16 v[82:85], v[134:137], v[214:217], v[82:85]
	v_mfma_f32_16x16x32_bf16 v[18:21], v[138:141], v[196:199], v[18:21]
	v_mfma_f32_16x16x32_bf16 v[18:21], v[142:145], v[214:217], v[18:21]
	v_mfma_f32_16x16x32_bf16 v[74:77], v[130:133], v[218:221], v[74:77]
	v_mfma_f32_16x16x32_bf16 v[74:77], v[134:137], v[222:225], v[74:77]
	v_mfma_f32_16x16x32_bf16 v[10:13], v[138:141], v[218:221], v[10:13]
	v_mfma_f32_16x16x32_bf16 v[10:13], v[142:145], v[222:225], v[10:13]
	v_mfma_f32_16x16x32_bf16 v[86:89], v[146:149], v[162:165], v[86:89]
	v_mfma_f32_16x16x32_bf16 v[86:89], v[150:153], v[166:169], v[86:89]
	v_mfma_f32_16x16x32_bf16 v[22:25], v[154:157], v[162:165], v[22:25]
	v_mfma_f32_16x16x32_bf16 v[22:25], v[158:161], v[166:169], v[22:25]
	v_mfma_f32_16x16x32_bf16 v[78:81], v[146:149], v[188:191], v[78:81]
	v_mfma_f32_16x16x32_bf16 v[78:81], v[150:153], v[192:195], v[78:81]
	v_mfma_f32_16x16x32_bf16 v[14:17], v[154:157], v[188:191], v[14:17]
	v_mfma_f32_16x16x32_bf16 v[14:17], v[158:161], v[192:195], v[14:17]
	v_mfma_f32_16x16x32_bf16 v[70:73], v[146:149], v[196:199], v[70:73]
	v_mfma_f32_16x16x32_bf16 v[70:73], v[150:153], v[214:217], v[70:73]
	v_mfma_f32_16x16x32_bf16 v[6:9], v[154:157], v[196:199], v[6:9]
	v_mfma_f32_16x16x32_bf16 v[6:9], v[158:161], v[214:217], v[6:9]
	v_mfma_f32_16x16x32_bf16 v[66:69], v[146:149], v[218:221], v[66:69]
	v_mfma_f32_16x16x32_bf16 v[66:69], v[150:153], v[222:225], v[66:69]
	v_mfma_f32_16x16x32_bf16 v[2:5], v[154:157], v[218:221], v[2:5]
	v_mfma_f32_16x16x32_bf16 v[2:5], v[158:161], v[222:225], v[2:5]
	s_setprio 0
	s_barrier
	ds_read_b128 v[130:133], v226
	ds_read_b128 v[134:137], v226 offset:1024
	ds_read_b128 v[138:141], v226 offset:2048
	ds_read_b128 v[142:145], v226 offset:3072
	ds_read_b128 v[146:149], v227
	ds_read_b128 v[150:153], v227 offset:1024
	ds_read_b128 v[154:157], v227 offset:2048
	ds_read_b128 v[158:161], v227 offset:3072
	ds_read_b128 v[162:165], v212 offset:32768
	ds_read_b128 v[166:169], v212 offset:33792
	ds_read_b128 v[188:191], v212 offset:34816
	ds_read_b128 v[192:195], v212 offset:35840
	ds_read_b128 v[196:199], v212 offset:36864
	ds_read_b128 v[214:217], v212 offset:37888
	s_add_i32 m0, s39, 0x4000
	ds_read_b128 v[218:221], v212 offset:38912
	global_load_lds_dwordx4 v170, s[100:101]
	s_add_i32 m0, s39, 0x6000
	ds_read_b128 v[222:225], v212 offset:39936
	global_load_lds_dwordx4 v174, s[100:101]
	s_waitcnt vmcnt(8) lgkmcnt(0)
	s_barrier
	s_setprio 1
	v_mfma_f32_16x16x32_bf16 v[126:129], v[130:133], v[162:165], v[126:129]
	v_mfma_f32_16x16x32_bf16 v[126:129], v[134:137], v[166:169], v[126:129]
	v_mfma_f32_16x16x32_bf16 v[62:65], v[138:141], v[162:165], v[62:65]
	v_mfma_f32_16x16x32_bf16 v[62:65], v[142:145], v[166:169], v[62:65]
	v_mfma_f32_16x16x32_bf16 v[122:125], v[130:133], v[188:191], v[122:125]
	v_mfma_f32_16x16x32_bf16 v[122:125], v[134:137], v[192:195], v[122:125]
	v_mfma_f32_16x16x32_bf16 v[58:61], v[138:141], v[188:191], v[58:61]
	v_mfma_f32_16x16x32_bf16 v[58:61], v[142:145], v[192:195], v[58:61]
	v_mfma_f32_16x16x32_bf16 v[110:113], v[130:133], v[196:199], v[110:113]
	v_mfma_f32_16x16x32_bf16 v[110:113], v[134:137], v[214:217], v[110:113]
	v_mfma_f32_16x16x32_bf16 v[50:53], v[138:141], v[196:199], v[50:53]
	v_mfma_f32_16x16x32_bf16 v[50:53], v[142:145], v[214:217], v[50:53]
	v_mfma_f32_16x16x32_bf16 v[106:109], v[130:133], v[218:221], v[106:109]
	v_mfma_f32_16x16x32_bf16 v[106:109], v[134:137], v[222:225], v[106:109]
	v_mfma_f32_16x16x32_bf16 v[42:45], v[138:141], v[218:221], v[42:45]
	v_mfma_f32_16x16x32_bf16 v[42:45], v[142:145], v[222:225], v[42:45]
	v_mfma_f32_16x16x32_bf16 v[118:121], v[146:149], v[162:165], v[118:121]
	v_mfma_f32_16x16x32_bf16 v[118:121], v[150:153], v[166:169], v[118:121]
	v_mfma_f32_16x16x32_bf16 v[54:57], v[154:157], v[162:165], v[54:57]
	v_mfma_f32_16x16x32_bf16 v[54:57], v[158:161], v[166:169], v[54:57]
	v_mfma_f32_16x16x32_bf16 v[114:117], v[146:149], v[188:191], v[114:117]
	v_mfma_f32_16x16x32_bf16 v[114:117], v[150:153], v[192:195], v[114:117]
	v_mfma_f32_16x16x32_bf16 v[46:49], v[154:157], v[188:191], v[46:49]
	v_mfma_f32_16x16x32_bf16 v[46:49], v[158:161], v[192:195], v[46:49]
	v_mfma_f32_16x16x32_bf16 v[102:105], v[146:149], v[196:199], v[102:105]
	v_mfma_f32_16x16x32_bf16 v[102:105], v[150:153], v[214:217], v[102:105]
	v_mfma_f32_16x16x32_bf16 v[38:41], v[154:157], v[196:199], v[38:41]
	v_mfma_f32_16x16x32_bf16 v[38:41], v[158:161], v[214:217], v[38:41]
	v_mfma_f32_16x16x32_bf16 v[98:101], v[146:149], v[218:221], v[98:101]
	v_mfma_f32_16x16x32_bf16 v[98:101], v[150:153], v[222:225], v[98:101]
	v_mfma_f32_16x16x32_bf16 v[34:37], v[154:157], v[218:221], v[34:37]
	v_mfma_f32_16x16x32_bf16 v[34:37], v[158:161], v[222:225], v[34:37]
	s_setprio 0
	s_barrier
	ds_read_b128 v[162:165], v212 offset:49152
	ds_read_b128 v[166:169], v212 offset:50176
	s_add_i32 m0, s39, 0x17f80
	ds_read_b128 v[188:191], v212 offset:51200
	global_load_lds_dwordx4 v172, s[92:93] offset:128
	s_add_i32 m0, s39, 0x19f80
	ds_read_b128 v[192:195], v212 offset:52224
	global_load_lds_dwordx4 v176, s[92:93] offset:128
	s_add_i32 m0, s39, 0x1bf80
	ds_read_b128 v[196:199], v212 offset:53248
	global_load_lds_dwordx4 v172, s[98:99] offset:128
	s_add_i32 m0, s39, 0x1df80
	ds_read_b128 v[214:217], v212 offset:54272
	global_load_lds_dwordx4 v176, s[98:99] offset:128
	s_add_i32 m0, s39, 0x7f80
	ds_read_b128 v[218:221], v212 offset:55296
	global_load_lds_dwordx4 v170, s[94:95] offset:128
	s_add_i32 m0, s39, 0x9f80
	ds_read_b128 v[222:225], v212 offset:56320
	global_load_lds_dwordx4 v174, s[94:95] offset:128
	s_waitcnt vmcnt(8) lgkmcnt(0)
	s_barrier
	s_setprio 1
	v_mfma_f32_16x16x32_bf16 v[94:97], v[130:133], v[162:165], v[94:97]
	v_mfma_f32_16x16x32_bf16 v[94:97], v[134:137], v[166:169], v[94:97]
	v_mfma_f32_16x16x32_bf16 v[30:33], v[138:141], v[162:165], v[30:33]
	v_mfma_f32_16x16x32_bf16 v[30:33], v[142:145], v[166:169], v[30:33]
	v_mfma_f32_16x16x32_bf16 v[90:93], v[130:133], v[188:191], v[90:93]
	v_mfma_f32_16x16x32_bf16 v[90:93], v[134:137], v[192:195], v[90:93]
	v_mfma_f32_16x16x32_bf16 v[26:29], v[138:141], v[188:191], v[26:29]
	v_mfma_f32_16x16x32_bf16 v[26:29], v[142:145], v[192:195], v[26:29]
	v_mfma_f32_16x16x32_bf16 v[82:85], v[130:133], v[196:199], v[82:85]
	v_mfma_f32_16x16x32_bf16 v[82:85], v[134:137], v[214:217], v[82:85]
	v_mfma_f32_16x16x32_bf16 v[18:21], v[138:141], v[196:199], v[18:21]
	v_mfma_f32_16x16x32_bf16 v[18:21], v[142:145], v[214:217], v[18:21]
	v_mfma_f32_16x16x32_bf16 v[74:77], v[130:133], v[218:221], v[74:77]
	v_mfma_f32_16x16x32_bf16 v[74:77], v[134:137], v[222:225], v[74:77]
	v_mfma_f32_16x16x32_bf16 v[10:13], v[138:141], v[218:221], v[10:13]
	v_mfma_f32_16x16x32_bf16 v[10:13], v[142:145], v[222:225], v[10:13]
	v_mfma_f32_16x16x32_bf16 v[86:89], v[146:149], v[162:165], v[86:89]
	v_mfma_f32_16x16x32_bf16 v[86:89], v[150:153], v[166:169], v[86:89]
	v_mfma_f32_16x16x32_bf16 v[22:25], v[154:157], v[162:165], v[22:25]
	v_mfma_f32_16x16x32_bf16 v[22:25], v[158:161], v[166:169], v[22:25]
	v_mfma_f32_16x16x32_bf16 v[78:81], v[146:149], v[188:191], v[78:81]
	v_mfma_f32_16x16x32_bf16 v[78:81], v[150:153], v[192:195], v[78:81]
	v_mfma_f32_16x16x32_bf16 v[14:17], v[154:157], v[188:191], v[14:17]
	v_mfma_f32_16x16x32_bf16 v[14:17], v[158:161], v[192:195], v[14:17]
	v_mfma_f32_16x16x32_bf16 v[70:73], v[146:149], v[196:199], v[70:73]
	v_mfma_f32_16x16x32_bf16 v[70:73], v[150:153], v[214:217], v[70:73]
	v_mfma_f32_16x16x32_bf16 v[6:9], v[154:157], v[196:199], v[6:9]
	s_add_i32 s66, s66, 2
	v_mfma_f32_16x16x32_bf16 v[6:9], v[158:161], v[214:217], v[6:9]
	s_add_u32 vcc_lo, vcc_lo, 0x100
	v_mfma_f32_16x16x32_bf16 v[66:69], v[146:149], v[218:221], v[66:69]
	s_addc_u32 vcc_hi, vcc_hi, 0
	v_mfma_f32_16x16x32_bf16 v[66:69], v[150:153], v[222:225], v[66:69]
	s_mov_b64 s[88:89], s[90:91]
	v_mfma_f32_16x16x32_bf16 v[2:5], v[154:157], v[218:221], v[2:5]
	s_cmp_gt_u32 s66, 61
	v_mfma_f32_16x16x32_bf16 v[2:5], v[158:161], v[222:225], v[2:5]
	s_setprio 0
	s_barrier
	s_cbranch_scc0 .LBB0_651
	s_and_b64 vcc, exec, s[36:37]
	s_cbranch_vccz .LBB0_654
	s_barrier

.LBB0_834:
	ds_read_b128 v[146:149], v152
	ds_read_b128 v[156:159], v152 offset:1024
	ds_read_b128 v[160:163], v152 offset:2048
	ds_read_b128 v[164:167], v152 offset:3072
	ds_read_b128 v[168:171], v153
	ds_read_b128 v[172:175], v153 offset:1024
	ds_read_b128 v[176:179], v153 offset:2048
	ds_read_b128 v[180:183], v153 offset:3072
	ds_read_b128 v[184:187], v154
	ds_read_b128 v[188:191], v154 offset:1024
	ds_read_b128 v[192:195], v154 offset:2048
	ds_read_b128 v[196:199], v154 offset:3072
	ds_read_b128 v[206:209], v154 offset:4096
	ds_read_b128 v[210:213], v154 offset:5120
	s_add_i32 m0, s1, 0xc000
	ds_read_b128 v[214:217], v154 offset:6144
	global_load_lds_dwordx4 v138, s[42:43]
	s_add_i32 m0, s1, 0xe000
	ds_read_b128 v[218:221], v154 offset:7168
	global_load_lds_dwordx4 v140, s[42:43]
	s_waitcnt vmcnt(8) lgkmcnt(0)
	s_barrier
	s_setprio 1
	v_mfma_f32_16x16x32_bf16 v[126:129], v[146:149], v[184:187], v[126:129]
	v_mfma_f32_16x16x32_bf16 v[126:129], v[156:159], v[188:191], v[126:129]
	v_mfma_f32_16x16x32_bf16 v[122:125], v[160:163], v[184:187], v[122:125]
	s_add_u32 s34, s42, 0x1fc000
	v_mfma_f32_16x16x32_bf16 v[122:125], v[164:167], v[188:191], v[122:125]
	s_addc_u32 s44, s43, 0
	v_mfma_f32_16x16x32_bf16 v[110:113], v[146:149], v[192:195], v[110:113]
	s_cmpk_eq_i32 s61, 0xa8
	v_mfma_f32_16x16x32_bf16 v[110:113], v[156:159], v[196:199], v[110:113]
	s_cselect_b32 s48, s41, s34
	v_mfma_f32_16x16x32_bf16 v[106:109], v[160:163], v[192:195], v[106:109]
	s_cselect_b32 s49, s23, s44
	v_mfma_f32_16x16x32_bf16 v[106:109], v[164:167], v[196:199], v[106:109]
	s_cselect_b32 s47, s21, s60
	v_mfma_f32_16x16x32_bf16 v[94:97], v[146:149], v[206:209], v[94:97]
	s_cselect_b32 s46, s58, s59
	v_mfma_f32_16x16x32_bf16 v[94:97], v[156:159], v[210:213], v[94:97]
	s_add_u32 s44, s48, 0x200000
	v_mfma_f32_16x16x32_bf16 v[90:93], v[160:163], v[206:209], v[90:93]
	s_addc_u32 s45, s49, 0
	v_mfma_f32_16x16x32_bf16 v[90:93], v[164:167], v[210:213], v[90:93]
	s_add_u32 s62, s46, 0x4000
	v_mfma_f32_16x16x32_bf16 v[78:81], v[146:149], v[214:217], v[78:81]
	s_addc_u32 s63, s47, 0
	v_mfma_f32_16x16x32_bf16 v[78:81], v[156:159], v[218:221], v[78:81]
	s_add_u32 s100, s48, 0x4000
	v_mfma_f32_16x16x32_bf16 v[74:77], v[160:163], v[214:217], v[74:77]
	s_addc_u32 s101, s49, 0
	v_mfma_f32_16x16x32_bf16 v[74:77], v[164:167], v[218:221], v[74:77]
	s_add_u32 s98, s46, 0x80000
	v_mfma_f32_16x16x32_bf16 v[118:121], v[168:171], v[184:187], v[118:121]
	s_addc_u32 s99, s47, 0
	v_mfma_f32_16x16x32_bf16 v[118:121], v[172:175], v[188:191], v[118:121]
	s_add_u32 s24, s46, 0x84000
	v_mfma_f32_16x16x32_bf16 v[114:117], v[176:179], v[184:187], v[114:117]
	s_addc_u32 s25, s47, 0
	v_mfma_f32_16x16x32_bf16 v[114:117], v[180:183], v[188:191], v[114:117]
	v_mfma_f32_16x16x32_bf16 v[102:105], v[168:171], v[192:195], v[102:105]
	v_mfma_f32_16x16x32_bf16 v[102:105], v[172:175], v[196:199], v[102:105]
	v_mfma_f32_16x16x32_bf16 v[98:101], v[176:179], v[192:195], v[98:101]
	v_mfma_f32_16x16x32_bf16 v[98:101], v[180:183], v[196:199], v[98:101]
	v_mfma_f32_16x16x32_bf16 v[86:89], v[168:171], v[206:209], v[86:89]
	v_mfma_f32_16x16x32_bf16 v[86:89], v[172:175], v[210:213], v[86:89]
	v_mfma_f32_16x16x32_bf16 v[82:85], v[176:179], v[206:209], v[82:85]
	v_mfma_f32_16x16x32_bf16 v[82:85], v[180:183], v[210:213], v[82:85]
	v_mfma_f32_16x16x32_bf16 v[70:73], v[168:171], v[214:217], v[70:73]
	v_mfma_f32_16x16x32_bf16 v[70:73], v[172:175], v[218:221], v[70:73]
	v_mfma_f32_16x16x32_bf16 v[66:69], v[176:179], v[214:217], v[66:69]
	v_mfma_f32_16x16x32_bf16 v[66:69], v[180:183], v[218:221], v[66:69]
	s_setprio 0
	s_barrier
	ds_read_b128 v[184:187], v154 offset:16384
	ds_read_b128 v[188:191], v154 offset:17408
	s_add_i32 m0, s1, 0x10000
	ds_read_b128 v[192:195], v154 offset:18432
	global_load_lds_dwordx4 v132, s[46:47]
	s_add_i32 m0, s1, 0x12000
	ds_read_b128 v[196:199], v154 offset:19456
	global_load_lds_dwordx4 v136, s[46:47]
	s_add_i32 m0, s1, 0x14000
	ds_read_b128 v[206:209], v154 offset:20480
	global_load_lds_dwordx4 v132, s[62:63]
	s_add_i32 m0, s1, 0x16000
	ds_read_b128 v[210:213], v154 offset:21504
	global_load_lds_dwordx4 v136, s[62:63]
	s_mov_b32 m0, s1
	ds_read_b128 v[214:217], v154 offset:22528
	global_load_lds_dwordx4 v130, s[48:49]
	s_add_i32 m0, s1, 0x2000
	ds_read_b128 v[218:221], v154 offset:23552
	global_load_lds_dwordx4 v134, s[48:49]
	s_waitcnt vmcnt(8) lgkmcnt(0)
	s_barrier
	s_setprio 1
	v_mfma_f32_16x16x32_bf16 v[62:65], v[146:149], v[184:187], v[62:65]
	v_mfma_f32_16x16x32_bf16 v[62:65], v[156:159], v[188:191], v[62:65]
	v_mfma_f32_16x16x32_bf16 v[58:61], v[160:163], v[184:187], v[58:61]
	v_mfma_f32_16x16x32_bf16 v[58:61], v[164:167], v[188:191], v[58:61]
	v_mfma_f32_16x16x32_bf16 v[46:49], v[146:149], v[192:195], v[46:49]
	v_mfma_f32_16x16x32_bf16 v[46:49], v[156:159], v[196:199], v[46:49]
	v_mfma_f32_16x16x32_bf16 v[42:45], v[160:163], v[192:195], v[42:45]
	v_mfma_f32_16x16x32_bf16 v[42:45], v[164:167], v[196:199], v[42:45]
	v_mfma_f32_16x16x32_bf16 v[30:33], v[146:149], v[206:209], v[30:33]
	v_mfma_f32_16x16x32_bf16 v[30:33], v[156:159], v[210:213], v[30:33]
	v_mfma_f32_16x16x32_bf16 v[26:29], v[160:163], v[206:209], v[26:29]
	v_mfma_f32_16x16x32_bf16 v[26:29], v[164:167], v[210:213], v[26:29]
	v_mfma_f32_16x16x32_bf16 v[14:17], v[146:149], v[214:217], v[14:17]
	v_mfma_f32_16x16x32_bf16 v[14:17], v[156:159], v[218:221], v[14:17]
	v_mfma_f32_16x16x32_bf16 v[10:13], v[160:163], v[214:217], v[10:13]
	v_mfma_f32_16x16x32_bf16 v[10:13], v[164:167], v[218:221], v[10:13]
	v_mfma_f32_16x16x32_bf16 v[54:57], v[168:171], v[184:187], v[54:57]
	v_mfma_f32_16x16x32_bf16 v[54:57], v[172:175], v[188:191], v[54:57]
	v_mfma_f32_16x16x32_bf16 v[50:53], v[176:179], v[184:187], v[50:53]
	v_mfma_f32_16x16x32_bf16 v[50:53], v[180:183], v[188:191], v[50:53]
	v_mfma_f32_16x16x32_bf16 v[38:41], v[168:171], v[192:195], v[38:41]
	v_mfma_f32_16x16x32_bf16 v[38:41], v[172:175], v[196:199], v[38:41]
	v_mfma_f32_16x16x32_bf16 v[34:37], v[176:179], v[192:195], v[34:37]
	v_mfma_f32_16x16x32_bf16 v[34:37], v[180:183], v[196:199], v[34:37]
	v_mfma_f32_16x16x32_bf16 v[22:25], v[168:171], v[206:209], v[22:25]
	v_mfma_f32_16x16x32_bf16 v[22:25], v[172:175], v[210:213], v[22:25]
	v_mfma_f32_16x16x32_bf16 v[18:21], v[176:179], v[206:209], v[18:21]
	v_mfma_f32_16x16x32_bf16 v[18:21], v[180:183], v[210:213], v[18:21]
	v_mfma_f32_16x16x32_bf16 v[6:9], v[168:171], v[214:217], v[6:9]
	v_mfma_f32_16x16x32_bf16 v[6:9], v[172:175], v[218:221], v[6:9]
	v_mfma_f32_16x16x32_bf16 v[2:5], v[176:179], v[214:217], v[2:5]
	v_mfma_f32_16x16x32_bf16 v[2:5], v[180:183], v[218:221], v[2:5]
	s_setprio 0
	s_barrier
	ds_read_b128 v[146:149], v226
	ds_read_b128 v[156:159], v226 offset:1024
	ds_read_b128 v[160:163], v226 offset:2048
	ds_read_b128 v[164:167], v226 offset:3072
	ds_read_b128 v[168:171], v227
	ds_read_b128 v[172:175], v227 offset:1024
	ds_read_b128 v[176:179], v227 offset:2048
	ds_read_b128 v[180:183], v227 offset:3072
	ds_read_b128 v[184:187], v154 offset:32768
	ds_read_b128 v[188:191], v154 offset:33792
	ds_read_b128 v[192:195], v154 offset:34816
	ds_read_b128 v[196:199], v154 offset:35840
	ds_read_b128 v[206:209], v154 offset:36864
	ds_read_b128 v[210:213], v154 offset:37888
	s_add_i32 m0, s1, 0x4000
	ds_read_b128 v[214:217], v154 offset:38912
	global_load_lds_dwordx4 v130, s[100:101]
	s_add_i32 m0, s1, 0x6000
	ds_read_b128 v[218:221], v154 offset:39936
	global_load_lds_dwordx4 v134, s[100:101]
	s_waitcnt vmcnt(8) lgkmcnt(0)
	s_barrier
	s_setprio 1
	v_mfma_f32_16x16x32_bf16 v[126:129], v[146:149], v[184:187], v[126:129]
	v_mfma_f32_16x16x32_bf16 v[126:129], v[156:159], v[188:191], v[126:129]
	v_mfma_f32_16x16x32_bf16 v[122:125], v[160:163], v[184:187], v[122:125]
	v_mfma_f32_16x16x32_bf16 v[122:125], v[164:167], v[188:191], v[122:125]
	v_mfma_f32_16x16x32_bf16 v[110:113], v[146:149], v[192:195], v[110:113]
	v_mfma_f32_16x16x32_bf16 v[110:113], v[156:159], v[196:199], v[110:113]
	v_mfma_f32_16x16x32_bf16 v[106:109], v[160:163], v[192:195], v[106:109]
	v_mfma_f32_16x16x32_bf16 v[106:109], v[164:167], v[196:199], v[106:109]
	v_mfma_f32_16x16x32_bf16 v[94:97], v[146:149], v[206:209], v[94:97]
	v_mfma_f32_16x16x32_bf16 v[94:97], v[156:159], v[210:213], v[94:97]
	v_mfma_f32_16x16x32_bf16 v[90:93], v[160:163], v[206:209], v[90:93]
	v_mfma_f32_16x16x32_bf16 v[90:93], v[164:167], v[210:213], v[90:93]
	v_mfma_f32_16x16x32_bf16 v[78:81], v[146:149], v[214:217], v[78:81]
	v_mfma_f32_16x16x32_bf16 v[78:81], v[156:159], v[218:221], v[78:81]
	v_mfma_f32_16x16x32_bf16 v[74:77], v[160:163], v[214:217], v[74:77]
	v_mfma_f32_16x16x32_bf16 v[74:77], v[164:167], v[218:221], v[74:77]
	v_mfma_f32_16x16x32_bf16 v[118:121], v[168:171], v[184:187], v[118:121]
	v_mfma_f32_16x16x32_bf16 v[118:121], v[172:175], v[188:191], v[118:121]
	v_mfma_f32_16x16x32_bf16 v[114:117], v[176:179], v[184:187], v[114:117]
	v_mfma_f32_16x16x32_bf16 v[114:117], v[180:183], v[188:191], v[114:117]
	v_mfma_f32_16x16x32_bf16 v[102:105], v[168:171], v[192:195], v[102:105]
	v_mfma_f32_16x16x32_bf16 v[102:105], v[172:175], v[196:199], v[102:105]
	v_mfma_f32_16x16x32_bf16 v[98:101], v[176:179], v[192:195], v[98:101]
	v_mfma_f32_16x16x32_bf16 v[98:101], v[180:183], v[196:199], v[98:101]
	v_mfma_f32_16x16x32_bf16 v[86:89], v[168:171], v[206:209], v[86:89]
	v_mfma_f32_16x16x32_bf16 v[86:89], v[172:175], v[210:213], v[86:89]
	v_mfma_f32_16x16x32_bf16 v[82:85], v[176:179], v[206:209], v[82:85]
	v_mfma_f32_16x16x32_bf16 v[82:85], v[180:183], v[210:213], v[82:85]
	v_mfma_f32_16x16x32_bf16 v[70:73], v[168:171], v[214:217], v[70:73]
	v_mfma_f32_16x16x32_bf16 v[70:73], v[172:175], v[218:221], v[70:73]
	v_mfma_f32_16x16x32_bf16 v[66:69], v[176:179], v[214:217], v[66:69]
	v_mfma_f32_16x16x32_bf16 v[66:69], v[180:183], v[218:221], v[66:69]
	s_setprio 0
	s_barrier
	ds_read_b128 v[184:187], v154 offset:49152
	ds_read_b128 v[188:191], v154 offset:50176
	s_add_i32 m0, s1, 0x18000
	ds_read_b128 v[192:195], v154 offset:51200
	global_load_lds_dwordx4 v132, s[98:99]
	s_add_i32 m0, s1, 0x1a000
	ds_read_b128 v[196:199], v154 offset:52224
	global_load_lds_dwordx4 v136, s[98:99]
	s_add_i32 m0, s1, 0x1c000
	ds_read_b128 v[206:209], v154 offset:53248
	global_load_lds_dwordx4 v132, s[24:25]
	s_add_i32 m0, s1, 0x1e000
	ds_read_b128 v[210:213], v154 offset:54272
	global_load_lds_dwordx4 v136, s[24:25]
	s_add_i32 m0, s1, 0x8000
	ds_read_b128 v[214:217], v154 offset:55296
	global_load_lds_dwordx4 v130, s[44:45]
	s_add_i32 m0, s1, 0xa000
	ds_read_b128 v[218:221], v154 offset:56320
	global_load_lds_dwordx4 v134, s[44:45]
	s_waitcnt vmcnt(8) lgkmcnt(0)
	s_barrier
	s_setprio 1
	v_mfma_f32_16x16x32_bf16 v[62:65], v[146:149], v[184:187], v[62:65]
	v_mfma_f32_16x16x32_bf16 v[62:65], v[156:159], v[188:191], v[62:65]
	v_mfma_f32_16x16x32_bf16 v[58:61], v[160:163], v[184:187], v[58:61]
	v_mfma_f32_16x16x32_bf16 v[58:61], v[164:167], v[188:191], v[58:61]
	v_mfma_f32_16x16x32_bf16 v[46:49], v[146:149], v[192:195], v[46:49]
	v_mfma_f32_16x16x32_bf16 v[46:49], v[156:159], v[196:199], v[46:49]
	v_mfma_f32_16x16x32_bf16 v[42:45], v[160:163], v[192:195], v[42:45]
	v_mfma_f32_16x16x32_bf16 v[42:45], v[164:167], v[196:199], v[42:45]
	v_mfma_f32_16x16x32_bf16 v[30:33], v[146:149], v[206:209], v[30:33]
	v_mfma_f32_16x16x32_bf16 v[30:33], v[156:159], v[210:213], v[30:33]
	v_mfma_f32_16x16x32_bf16 v[26:29], v[160:163], v[206:209], v[26:29]
	v_mfma_f32_16x16x32_bf16 v[26:29], v[164:167], v[210:213], v[26:29]
	v_mfma_f32_16x16x32_bf16 v[14:17], v[146:149], v[214:217], v[14:17]
	v_mfma_f32_16x16x32_bf16 v[14:17], v[156:159], v[218:221], v[14:17]
	v_mfma_f32_16x16x32_bf16 v[10:13], v[160:163], v[214:217], v[10:13]
	v_mfma_f32_16x16x32_bf16 v[10:13], v[164:167], v[218:221], v[10:13]
	v_mfma_f32_16x16x32_bf16 v[54:57], v[168:171], v[184:187], v[54:57]
	v_mfma_f32_16x16x32_bf16 v[54:57], v[172:175], v[188:191], v[54:57]
	v_mfma_f32_16x16x32_bf16 v[50:53], v[176:179], v[184:187], v[50:53]
	v_mfma_f32_16x16x32_bf16 v[50:53], v[180:183], v[188:191], v[50:53]
	v_mfma_f32_16x16x32_bf16 v[38:41], v[168:171], v[192:195], v[38:41]
	v_mfma_f32_16x16x32_bf16 v[38:41], v[172:175], v[196:199], v[38:41]
	v_mfma_f32_16x16x32_bf16 v[34:37], v[176:179], v[192:195], v[34:37]
	v_mfma_f32_16x16x32_bf16 v[34:37], v[180:183], v[196:199], v[34:37]
	v_mfma_f32_16x16x32_bf16 v[22:25], v[168:171], v[206:209], v[22:25]
	v_mfma_f32_16x16x32_bf16 v[22:25], v[172:175], v[210:213], v[22:25]
	s_add_i32 s61, s61, 2
	v_mfma_f32_16x16x32_bf16 v[18:21], v[176:179], v[206:209], v[18:21]
	s_add_u32 s59, s59, 0x100000
	v_mfma_f32_16x16x32_bf16 v[18:21], v[180:183], v[210:213], v[18:21]
	s_addc_u32 s60, s60, 0
	v_mfma_f32_16x16x32_bf16 v[6:9], v[168:171], v[214:217], v[6:9]
	s_add_u32 s42, s42, 0x400000
	v_mfma_f32_16x16x32_bf16 v[6:9], v[172:175], v[218:221], v[6:9]
	s_addc_u32 s43, s43, 0
	v_mfma_f32_16x16x32_bf16 v[2:5], v[176:179], v[214:217], v[2:5]
	s_cmpk_gt_u32 s61, 0xa9
	v_mfma_f32_16x16x32_bf16 v[2:5], v[180:183], v[218:221], v[2:5]
	s_setprio 0
	s_barrier
	s_cbranch_scc0 .LBB0_834
	s_and_b64 vcc, exec, s[18:19]
	s_cbranch_vccz .LBB0_837
	s_barrier
